# dropped fmax/fmin input-canonicalising v_max x,x ops and rebuilt the MoBA 32-value row-max trees with v_max3 (SB + MoBA tile loops)
# speedup vs baseline: 1.0052x; 1.0052x over previous
; #define LAS __attribute__((address_space(3)))
; DI float fast_exp2(float x) { return __builtin_amdgcn_exp2f(x); }
; DI float fast_rcp(float x) { return __builtin_amdgcn_rcpf(x); }
; DI void sb_wg_unit(bf16_t* act, int b, int hh, int Qb, LAS unsigned char* lds, volatile LAS unsigned* ctl, int tid, int wid, int lane) {
;     ...
;         while (!done && t >= t_bot) {
;             const int kv0 = t * 64;
;             LAS const unsigned char* Ks = lds + (t_top - t) * 16384; LAS const unsigned char* Vs = Ks + 8192;
;             f32x16 p0, p1;
; #pragma unroll
;             for (int i = 0; i < 16; ++i) { p0[i] = 0.f; p1[i] = 0.f; }
;             qk_tile(p0, p1, Ks, qf, r, h);
;             const bool diag = (kv0 + 63 >= q0);
;             f32x16 F0, F1;
; #pragma unroll
;             for (int i = 0; i < 16; ++i) {
;                 const int kl = (i & 3) + 8 * (i >> 2) + 4 * h;
;                 { const float e = fast_exp2(fminf(p0[i], 60.f)); const float f = fast_rcp(1.f + e);
;                   const bool valid = !diag || (kv0 + kl < qpos); F0[i] = valid ? f : 1.f; p0[i] = valid ? e * f : 0.f; }
;                 { const float e = fast_exp2(fminf(p1[i], 60.f)); const float f = fast_rcp(1.f + e);
;                   const bool valid = !diag || (kv0 + 32 + kl < qpos); F1[i] = valid ? f : 1.f; p1[i] = valid ? e * f : 0.f; }
;             }
.LBB0_355:
	v_add_u32_e32 v90, s13, v97
	ds_read_b128 v[34:37], v90
	ds_read_b128 v[38:41], v90 offset:512
	ds_read_b128 v[100:103], v90 offset:2048
	ds_read_b128 v[108:111], v90 offset:2560
	s_cmp_lt_i32 s12, s21
	s_cselect_b64 s[8:9], -1, 0
	s_waitcnt vmcnt(8) lgkmcnt(3)
	v_mfma_f32_32x32x16_bf16 v[50:65], v[34:37], v[66:69], 0
	s_mov_b32 s10, s24
	v_add_u32_e32 v97, 0x4000, v97
	s_waitcnt lgkmcnt(2)
	v_mfma_f32_32x32x16_bf16 v[34:49], v[38:41], v[66:69], 0
	s_waitcnt lgkmcnt(1)
	v_mfma_f32_32x32x16_bf16 v[50:65], v[100:103], v[70:73], v[50:65]
	s_waitcnt lgkmcnt(0)
	v_mfma_f32_32x32x16_bf16 v[34:49], v[108:111], v[70:73], v[34:49]
	ds_read_b128 v[100:103], v90 offset:4096
	ds_read_b128 v[108:111], v90 offset:4608
	s_waitcnt lgkmcnt(1)
	v_mfma_f32_32x32x16_bf16 v[50:65], v[100:103], v[74:77], v[50:65]
	s_waitcnt lgkmcnt(0)
	v_mfma_f32_32x32x16_bf16 v[34:49], v[108:111], v[74:77], v[34:49]
	ds_read_b128 v[100:103], v90 offset:6144
	ds_read_b128 v[108:111], v90 offset:6656
	v_add_u32_e32 v90, s12, v82
	v_subrev_u32_e32 v98, 63, v90
	v_cmp_lt_i32_e32 vcc, v98, v86
	s_or_b64 vcc, s[8:9], vcc
	s_waitcnt lgkmcnt(1)
	v_mfma_f32_32x32x16_bf16 v[50:65], v[100:103], v[78:81], v[50:65]
	v_subrev_u32_e32 v103, 30, v90
	s_waitcnt lgkmcnt(0)
	v_mfma_f32_32x32x16_bf16 v[34:49], v[108:111], v[78:81], v[34:49]
	s_nop 8
	v_min_f32_e32 v50, 0x42700000, v50
	v_exp_f32_e32 v100, v50
	s_nop 0
	v_add_f32_e32 v50, 1.0, v100
	v_min_f32_e32 v34, 0x42700000, v34
	v_rcp_f32_e32 v101, v50
	v_exp_f32_e32 v34, v34
	v_min_f32_e32 v35, 0x42700000, v35
	v_mul_f32_e32 v98, v100, v101
	v_add_f32_e32 v100, 1.0, v34
	v_rcp_f32_e32 v100, v100
	v_cndmask_b32_e32 v50, 1.0, v101, vcc
	v_subrev_u32_e32 v101, 31, v90
	v_cndmask_b32_e32 v98, 0, v98, vcc
	v_cmp_lt_i32_e32 vcc, v101, v86
	s_or_b64 vcc, s[8:9], vcc
	v_mul_f32_e32 v34, v34, v100
	v_cndmask_b32_e32 v101, 1.0, v100, vcc
	v_cndmask_b32_e32 v100, 0, v34, vcc
	v_min_f32_e32 v34, 0x42700000, v51
	v_exp_f32_e32 v51, v34
	v_exp_f32_e32 v35, v35
	v_add_f32_e32 v34, 1.0, v51
	v_rcp_f32_e32 v102, v34
	v_subrev_u32_e32 v34, 62, v90
	v_cmp_lt_i32_e32 vcc, v34, v86
	s_or_b64 vcc, s[8:9], vcc
	v_mul_f32_e32 v51, v51, v102
	v_cndmask_b32_e32 v34, 1.0, v102, vcc
	v_cndmask_b32_e32 v102, 0, v51, vcc
	v_add_f32_e32 v51, 1.0, v35
	v_rcp_f32_e32 v51, v51
	v_cmp_lt_i32_e32 vcc, v103, v86
	s_or_b64 vcc, s[8:9], vcc
	v_mul_f32_e32 v35, v35, v51
	v_cndmask_b32_e32 v104, 0, v35, vcc
	v_min_f32_e32 v35, 0x42700000, v52
	v_exp_f32_e32 v35, v35
	v_cndmask_b32_e32 v103, 1.0, v51, vcc
	v_subrev_u32_e32 v52, 61, v90
	v_cmp_lt_i32_e32 vcc, v52, v86
	v_add_f32_e32 v51, 1.0, v35
	v_rcp_f32_e32 v51, v51
	s_or_b64 vcc, s[8:9], vcc
	v_mul_f32_e32 v35, v35, v51
	v_cndmask_b32_e32 v105, 0, v35, vcc
	v_min_f32_e32 v35, 0x42700000, v36
	v_exp_f32_e32 v35, v35
	v_cndmask_b32_e32 v52, 1.0, v51, vcc
	v_subrev_u32_e32 v51, 29, v90
	v_cmp_lt_i32_e32 vcc, v51, v86
	v_add_f32_e32 v36, 1.0, v35
	v_rcp_f32_e32 v36, v36
	s_or_b64 vcc, s[8:9], vcc
	v_mul_f32_e32 v35, v35, v36
	v_cndmask_b32_e32 v108, 0, v35, vcc
	v_min_f32_e32 v35, 0x42700000, v53
	v_exp_f32_e32 v35, v35
	v_cndmask_b32_e32 v107, 1.0, v36, vcc
	v_add_f32_e32 v36, 1.0, v35
	v_rcp_f32_e32 v51, v36
	v_subrev_u32_e32 v36, 60, v90
	v_cmp_lt_i32_e32 vcc, v36, v86
	s_or_b64 vcc, s[8:9], vcc
	v_mul_f32_e32 v35, v35, v51
	v_cndmask_b32_e32 v109, 0, v35, vcc
	v_min_f32_e32 v35, 0x42700000, v37
	v_exp_f32_e32 v35, v35
	v_cndmask_b32_e32 v36, 1.0, v51, vcc
	v_subrev_u32_e32 v51, 28, v90
	v_cmp_lt_i32_e32 vcc, v51, v86
	v_add_f32_e32 v37, 1.0, v35
	v_rcp_f32_e32 v37, v37
	s_or_b64 vcc, s[8:9], vcc
	v_subrev_u32_e32 v51, 55, v90
	v_mul_f32_e32 v35, v35, v37
	v_cndmask_b32_e32 v111, 0, v35, vcc
	v_min_f32_e32 v35, 0x42700000, v54
	v_exp_f32_e32 v35, v35
	v_cndmask_b32_e32 v110, 1.0, v37, vcc
	v_cmp_lt_i32_e32 vcc, v51, v86
	s_or_b64 vcc, s[8:9], vcc
	v_add_f32_e32 v37, 1.0, v35
	v_rcp_f32_e32 v37, v37
	s_nop 0
	v_mul_f32_e32 v35, v35, v37
	v_cndmask_b32_e32 v54, 0, v35, vcc
	v_min_f32_e32 v35, 0x42700000, v38
	v_exp_f32_e32 v35, v35
	v_cndmask_b32_e32 v51, 1.0, v37, vcc
	v_subrev_u32_e32 v38, 23, v90
	v_cmp_lt_i32_e32 vcc, v38, v86
	v_add_f32_e32 v37, 1.0, v35
	v_rcp_f32_e32 v37, v37
	s_or_b64 vcc, s[8:9], vcc
	v_subrev_u32_e32 v38, 54, v90
	v_mul_f32_e32 v35, v35, v37
	v_cndmask_b32_e32 v112, 0, v35, vcc
	v_min_f32_e32 v35, 0x42700000, v55
	v_exp_f32_e32 v35, v35
	v_cndmask_b32_e32 v53, 1.0, v37, vcc
	v_cmp_lt_i32_e32 vcc, v38, v86
	s_or_b64 vcc, s[8:9], vcc
	v_add_f32_e32 v37, 1.0, v35
	v_rcp_f32_e32 v37, v37
	v_subrev_u32_e32 v38, 22, v90
	v_mul_f32_e32 v35, v35, v37
	v_cndmask_b32_e32 v113, 0, v35, vcc
	v_min_f32_e32 v35, 0x42700000, v39
	v_exp_f32_e32 v35, v35
	v_cndmask_b32_e32 v55, 1.0, v37, vcc
	v_cmp_lt_i32_e32 vcc, v38, v86
	s_or_b64 vcc, s[8:9], vcc
	v_add_f32_e32 v37, 1.0, v35
	v_rcp_f32_e32 v37, v37
	v_subrev_u32_e32 v38, 53, v90
	v_mul_f32_e32 v35, v35, v37
	v_cndmask_b32_e32 v115, 0, v35, vcc
	v_min_f32_e32 v35, 0x42700000, v56
	v_exp_f32_e32 v35, v35
	v_cndmask_b32_e32 v114, 1.0, v37, vcc
	v_cmp_lt_i32_e32 vcc, v38, v86
	s_or_b64 vcc, s[8:9], vcc
	v_add_f32_e32 v37, 1.0, v35
	v_rcp_f32_e32 v37, v37
	v_subrev_u32_e32 v38, 21, v90
	v_mul_f32_e32 v35, v35, v37
	v_cndmask_b32_e32 v117, 0, v35, vcc
	v_min_f32_e32 v35, 0x42700000, v40
	v_exp_f32_e32 v35, v35
	v_cndmask_b32_e32 v116, 1.0, v37, vcc
	v_cmp_lt_i32_e32 vcc, v38, v86
	s_or_b64 vcc, s[8:9], vcc
	v_add_f32_e32 v37, 1.0, v35
	v_rcp_f32_e32 v37, v37
	v_subrev_u32_e32 v38, 52, v90
	v_mul_f32_e32 v35, v35, v37
	v_cndmask_b32_e32 v119, 0, v35, vcc
	v_min_f32_e32 v35, 0x42700000, v57
	v_exp_f32_e32 v35, v35
	v_cndmask_b32_e32 v118, 1.0, v37, vcc
; DI float fast_exp2(float x) { return __builtin_amdgcn_exp2f(x); }
; DI float fast_rcp(float x) { return __builtin_amdgcn_rcpf(x); }
; DI void sb_wg_unit(bf16_t* act, int b, int hh, int Qb, LAS unsigned char* lds, volatile LAS unsigned* ctl, int tid, int wid, int lane) {
;     ...
;             for (int i = 0; i < 16; ++i) {
;                 const int kl = (i & 3) + 8 * (i >> 2) + 4 * h;
;                 { const float e = fast_exp2(fminf(p0[i], 60.f)); const float f = fast_rcp(1.f + e);
;                   const bool valid = !diag || (kv0 + kl < qpos); F0[i] = valid ? f : 1.f; p0[i] = valid ? e * f : 0.f; }
;                 { const float e = fast_exp2(fminf(p1[i], 60.f)); const float f = fast_rcp(1.f + e);
;                   const bool valid = !diag || (kv0 + 32 + kl < qpos); F1[i] = valid ? f : 1.f; p1[i] = valid ? e * f : 0.f; }
;             }
;             float G[8], Go[8];
; #pragma unroll
;             for (int g = 0; g < 4; ++g) { G[g] = (F0[4 * g] * F0[4 * g + 1]) * (F0[4 * g + 2] * F0[4 * g + 3]); G[4 + g] = (F1[4 * g] * F1[4 * g + 1]) * (F1[4 * g + 2] * F1[4 * g + 3]); }
	v_cmp_lt_i32_e32 vcc, v38, v86
	s_or_b64 vcc, s[8:9], vcc
	v_add_f32_e32 v37, 1.0, v35
	v_rcp_f32_e32 v37, v37
	v_subrev_u32_e32 v38, 20, v90
	v_mul_f32_e32 v35, v35, v37
	v_cndmask_b32_e32 v121, 0, v35, vcc
	v_min_f32_e32 v35, 0x42700000, v41
	v_exp_f32_e32 v35, v35
	v_cndmask_b32_e32 v120, 1.0, v37, vcc
	v_cmp_lt_i32_e32 vcc, v38, v86
	s_or_b64 vcc, s[8:9], vcc
	v_add_f32_e32 v37, 1.0, v35
	v_rcp_f32_e32 v37, v37
	v_subrev_u32_e32 v38, 47, v90
	v_subrev_u32_e32 v41, 45, v90
	v_mul_f32_e32 v35, v35, v37
	v_cndmask_b32_e32 v123, 0, v35, vcc
	v_min_f32_e32 v35, 0x42700000, v58
	v_exp_f32_e32 v35, v35
	v_cndmask_b32_e32 v122, 1.0, v37, vcc
	v_cmp_lt_i32_e32 vcc, v38, v86
	s_or_b64 vcc, s[8:9], vcc
	v_add_f32_e32 v37, 1.0, v35
	v_rcp_f32_e32 v37, v37
	v_add_u32_e32 v38, -15, v90
	v_mul_f32_e32 v35, v35, v37
	v_cndmask_b32_e32 v124, 0, v35, vcc
	v_min_f32_e32 v35, 0x42700000, v42
	v_exp_f32_e32 v35, v35
	v_cndmask_b32_e32 v39, 1.0, v37, vcc
	v_cmp_lt_i32_e32 vcc, v38, v86
	s_or_b64 vcc, s[8:9], vcc
	v_add_f32_e32 v37, 1.0, v35
	v_rcp_f32_e32 v37, v37
	v_subrev_u32_e32 v38, 46, v90
	v_mul_f32_e32 v35, v35, v37
	v_cndmask_b32_e32 v125, 0, v35, vcc
	v_min_f32_e32 v35, 0x42700000, v59
	v_exp_f32_e32 v35, v35
	v_cndmask_b32_e32 v40, 1.0, v37, vcc
	v_cmp_lt_i32_e32 vcc, v38, v86
	s_or_b64 vcc, s[8:9], vcc
	v_add_f32_e32 v37, 1.0, v35
	v_rcp_f32_e32 v37, v37
	v_add_u32_e32 v38, -14, v90
	v_mul_f32_e32 v35, v35, v37
	v_cndmask_b32_e32 v127, 0, v35, vcc
	v_min_f32_e32 v35, 0x42700000, v43
	v_exp_f32_e32 v35, v35
	v_cndmask_b32_e32 v126, 1.0, v37, vcc
	v_cmp_lt_i32_e32 vcc, v38, v86
	s_or_b64 vcc, s[8:9], vcc
	v_add_f32_e32 v37, 1.0, v35
	v_rcp_f32_e32 v37, v37
	v_subrev_u32_e32 v43, 38, v90
	v_mul_f32_e32 v35, v35, v37
	v_cndmask_b32_e32 v128, 0, v35, vcc
	v_min_f32_e32 v35, 0x42700000, v60
	v_exp_f32_e32 v35, v35
	v_cndmask_b32_e32 v38, 1.0, v37, vcc
	v_cmp_lt_i32_e32 vcc, v41, v86
	s_or_b64 vcc, s[8:9], vcc
	v_add_f32_e32 v37, 1.0, v35
	v_rcp_f32_e32 v37, v37
	v_add_u32_e32 v41, -13, v90
	v_mul_f32_e32 v35, v35, v37
	v_cndmask_b32_e32 v130, 0, v35, vcc
	v_min_f32_e32 v35, 0x42700000, v44
	v_exp_f32_e32 v35, v35
	v_cndmask_b32_e32 v129, 1.0, v37, vcc
	v_cmp_lt_i32_e32 vcc, v41, v86
	s_or_b64 vcc, s[8:9], vcc
	v_add_f32_e32 v37, 1.0, v35
	v_rcp_f32_e32 v37, v37
	v_subrev_u32_e32 v41, 44, v90
	v_mul_f32_e32 v35, v35, v37
	v_cndmask_b32_e32 v132, 0, v35, vcc
	v_min_f32_e32 v35, 0x42700000, v61
	v_exp_f32_e32 v35, v35
	v_cndmask_b32_e32 v131, 1.0, v37, vcc
	v_cmp_lt_i32_e32 vcc, v41, v86
	s_or_b64 vcc, s[8:9], vcc
	v_add_f32_e32 v37, 1.0, v35
	v_rcp_f32_e32 v37, v37
	v_add_u32_e32 v41, -12, v90
	v_mul_f32_e32 v35, v35, v37
	v_cndmask_b32_e32 v134, 0, v35, vcc
	v_min_f32_e32 v35, 0x42700000, v45
	v_exp_f32_e32 v35, v35
	v_cndmask_b32_e32 v133, 1.0, v37, vcc
	v_cmp_lt_i32_e32 vcc, v41, v86
	s_or_b64 vcc, s[8:9], vcc
	v_add_f32_e32 v37, 1.0, v35
	v_rcp_f32_e32 v37, v37
	v_subrev_u32_e32 v41, 39, v90
	v_mul_f32_e32 v35, v35, v37
	v_cndmask_b32_e32 v136, 0, v35, vcc
	v_min_f32_e32 v35, 0x42700000, v62
	v_exp_f32_e32 v35, v35
	v_cndmask_b32_e32 v135, 1.0, v37, vcc
	v_cmp_lt_i32_e32 vcc, v41, v86
	s_or_b64 vcc, s[8:9], vcc
	v_add_f32_e32 v37, 1.0, v35
	v_rcp_f32_e32 v37, v37
	v_add_u32_e32 v41, -7, v90
	v_mul_f32_e32 v44, v131, v135
	v_mul_f32_e32 v35, v35, v37
	v_cndmask_b32_e32 v137, 0, v35, vcc
	v_min_f32_e32 v35, 0x42700000, v46
	v_exp_f32_e32 v35, v35
	v_cndmask_b32_e32 v42, 1.0, v37, vcc
	v_cmp_lt_i32_e32 vcc, v41, v86
	s_or_b64 vcc, s[8:9], vcc
	v_add_f32_e32 v37, 1.0, v35
	v_rcp_f32_e32 v37, v37
	s_nop 0
	v_mul_f32_e32 v35, v35, v37
	v_cndmask_b32_e32 v138, 0, v35, vcc
	v_min_f32_e32 v35, 0x42700000, v63
	v_exp_f32_e32 v35, v35
	v_cndmask_b32_e32 v41, 1.0, v37, vcc
	v_cmp_lt_i32_e32 vcc, v43, v86
	s_or_b64 vcc, s[8:9], vcc
	v_add_f32_e32 v37, 1.0, v35
	v_rcp_f32_e32 v37, v37
	v_add_u32_e32 v43, -6, v90
	v_mul_f32_e32 v35, v35, v37
	v_cndmask_b32_e32 v139, 0, v35, vcc
	v_min_f32_e32 v35, 0x42700000, v47
	v_exp_f32_e32 v35, v35
	v_cndmask_b32_e32 v56, 1.0, v37, vcc
	v_cmp_lt_i32_e32 vcc, v43, v86
	s_or_b64 vcc, s[8:9], vcc
	v_add_f32_e32 v37, 1.0, v35
	v_rcp_f32_e32 v37, v37
	v_subrev_u32_e32 v43, 37, v90
	v_mul_f32_e32 v35, v35, v37
	v_cndmask_b32_e32 v141, 0, v35, vcc
	v_min_f32_e32 v35, 0x42700000, v64
	v_exp_f32_e32 v35, v35
	v_cndmask_b32_e32 v140, 1.0, v37, vcc
	v_cmp_lt_i32_e32 vcc, v43, v86
	s_or_b64 vcc, s[8:9], vcc
	v_add_f32_e32 v37, 1.0, v35
	v_rcp_f32_e32 v37, v37
	v_add_u32_e32 v43, -5, v90
	v_mul_f32_e32 v41, v41, v140
	v_mul_f32_e32 v35, v35, v37
	v_cndmask_b32_e32 v63, 0, v35, vcc
	v_min_f32_e32 v35, 0x42700000, v48
	v_exp_f32_e32 v35, v35
	v_cndmask_b32_e32 v58, 1.0, v37, vcc
	v_cmp_lt_i32_e32 vcc, v43, v86
	s_or_b64 vcc, s[8:9], vcc
	v_add_f32_e32 v37, 1.0, v35
	v_rcp_f32_e32 v37, v37
	v_subrev_u32_e32 v43, 36, v90
	v_mul_f32_e32 v35, v35, v37
	v_cndmask_b32_e32 v143, 0, v35, vcc
	v_min_f32_e32 v35, 0x42700000, v65
	v_exp_f32_e32 v35, v35
	v_cndmask_b32_e32 v142, 1.0, v37, vcc
	v_cmp_lt_i32_e32 vcc, v43, v86
	s_or_b64 vcc, s[8:9], vcc
	v_add_f32_e32 v37, 1.0, v35
	v_rcp_f32_e32 v37, v37
	v_add_u32_e32 v43, -4, v90
	v_mul_f32_e32 v35, v35, v37
	v_cndmask_b32_e32 v62, 0, v35, vcc
	v_min_f32_e32 v35, 0x42700000, v49
	v_exp_f32_e32 v35, v35
	v_cndmask_b32_e32 v60, 1.0, v37, vcc
	v_cmp_lt_i32_e32 vcc, v43, v86
	s_or_b64 vcc, s[8:9], vcc
	v_add_f32_e32 v37, 1.0, v35
	v_rcp_f32_e32 v37, v37
	s_mov_b32 s8, 0x800000
	v_mul_f32_e32 v35, v35, v37
	v_cndmask_b32_e32 v144, 1.0, v37, vcc
	v_cndmask_b32_e32 v145, 0, v35, vcc
	v_mul_f32_e32 v35, v101, v103
	v_mul_f32_e32 v37, v107, v110
	v_mul_f32_e32 v43, v35, v37
	v_mul_f32_e32 v35, v51, v55
; #define LAS __attribute__((address_space(3)))
; #define MFMA32(a, b, c) __builtin_amdgcn_mfma_f32_32x32x16_bf16((a), (b), (c), 0, 0, 0)
; DI void pv_tile(f32x16& o0, f32x16& o1, LAS const unsigned char* Vs, const f32x16& p0, const f32x16& p1, int lane) {
;     const int h = lane >> 5;
;     LAS const unsigned char* vb = Vs + (4 * h + ((lane & 15) >> 2)) * 64 + ((lane >> 4) & 1) * 32 + (lane & 3) * 8;
; #pragma unroll
;     for (int kh = 0; kh < 2; ++kh)
; #pragma unroll
;         for (int s2 = 0; s2 < 2; ++s2) {
;             const bf16x8 pb = kh ? pack8(p1, s2) : pack8(p0, s2);
;             const int ro = (32 * kh + 16 * s2) * 64;
;             const s16x4 l0 = vtr(vb + ro), h0 = vtr(vb + ro + 512), l1 = vtr(vb + 4096 + ro), h1 = vtr(vb + 4096 + ro + 512);
;             const bf16x8 v0 = (bf16x8){l0[0], l0[1], l0[2], l0[3], h0[0], h0[1], h0[2], h0[3]};
;             const bf16x8 v1 = (bf16x8){l1[0], l1[1], l1[2], l1[3], h1[0], h1[1], h1[2], h1[3]};
;             o0 = MFMA32(v0, pb, o0); o1 = MFMA32(v1, pb, o1);
;         }
; DI void sb_wg_unit(bf16_t* act, int b, int hh, int Qb, LAS unsigned char* lds, volatile LAS unsigned* ctl, int tid, int wid, int lane) {
;     ...
;             float G[8], Go[8];
; #pragma unroll
;             for (int g = 0; g < 4; ++g) { G[g] = (F0[4 * g] * F0[4 * g + 1]) * (F0[4 * g + 2] * F0[4 * g + 3]); G[4 + g] = (F1[4 * g] * F1[4 * g + 1]) * (F1[4 * g + 2] * F1[4 * g + 3]); }
; #pragma unroll
;             for (int g = 0; g < 8; ++g) Go[g] = xhalf_other(G[g]);
;             float run = C; float A[8];
; #pragma unroll
;             for (int g = 7; g >= 0; --g) { A[g] = run * (h == 0 ? Go[g] : 1.f); run *= (G[g] * Go[g]); }
; #pragma unroll
;             for (int g = 0; g < 4; ++g) {
;                 { float bt = A[g]; p0[4 * g + 3] *= bt; bt *= F0[4 * g + 3]; p0[4 * g + 2] *= bt; bt *= F0[4 * g + 2]; p0[4 * g + 1] *= bt; bt *= F0[4 * g + 1]; p0[4 * g] *= bt; }
;                 { float bt = A[4 + g]; p1[4 * g + 3] *= bt; bt *= F1[4 * g + 3]; p1[4 * g + 2] *= bt; bt *= F1[4 * g + 2]; p1[4 * g + 1] *= bt; bt *= F1[4 * g + 1]; p1[4 * g] *= bt; }
;             }
;             C = run;
;             pv_tile(o0, o1, Vs, p0, p1, lane);
;             if (__all(C < 1.17549435e-38f)) done = true;
;             --t;
	v_mul_f32_e32 v37, v116, v120
	v_mul_f32_e32 v51, v35, v37
	v_mul_f32_e32 v35, v53, v114
	v_mul_f32_e32 v37, v118, v122
	v_mul_f32_e32 v37, v35, v37
	v_mul_f32_e32 v35, v39, v126
	v_mul_f32_e32 v39, v129, v133
	v_mul_f32_e32 v46, v35, v39
	v_mov_b32_e32 v35, v51
	v_mov_b32_e32 v45, v51
	s_nop 1
	v_permlane32_swap_b32_e32 v35, v45
	v_xor_b32_e32 v35, v35, v45
	v_mov_b32_e32 v45, v46
	v_mov_b32_e32 v47, v46
	s_nop 1
	v_permlane32_swap_b32_e32 v45, v47
	v_xor_b32_e32 v45, v45, v47
	v_xor_b32_e32 v47, v45, v46
	v_mov_b32_e32 v45, v43
	v_mov_b32_e32 v48, v43
	s_nop 1
	v_permlane32_swap_b32_e32 v45, v48
	v_xor_b32_e32 v45, v45, v48
	v_xor_b32_e32 v57, v45, v43
	v_mov_b32_e32 v45, v37
	v_mov_b32_e32 v48, v37
	v_mul_f32_e32 v39, v142, v144
	s_nop 0
	v_permlane32_swap_b32_e32 v45, v48
	v_xor_b32_e32 v45, v45, v48
	v_pk_mul_f32 v[40:41], v[40:41], v[38:39]
	v_xor_b32_e32 v48, v45, v37
	v_mov_b32_e32 v39, v41
	v_mov_b32_e32 v45, v41
	s_nop 1
	v_permlane32_swap_b32_e32 v39, v45
	v_xor_b32_e32 v39, v39, v45
	v_xor_b32_e32 v45, v39, v41
	v_pk_mul_f32 v[40:41], v[40:41], v[44:45]
	v_mul_f32_e32 v59, v37, v48
	v_mov_b32_e32 v39, v40
	v_mov_b32_e32 v44, v40
	s_nop 1
	v_permlane32_swap_b32_e32 v39, v44
	v_xor_b32_e32 v39, v39, v44
	v_xor_b32_e32 v90, v39, v40
	v_cndmask_b32_e64 v39, 1.0, v45, s[42:43]
	v_mul_f32_e32 v101, v91, v39
	v_cndmask_b32_e64 v39, 1.0, v90, s[42:43]
	v_pk_mul_f32 v[40:41], v[40:41], v[90:91]
	v_pk_mul_f32 v[42:43], v[42:43], v[56:57]
	v_mul_f32_e32 v49, v39, v41
	v_pk_mul_f32 v[40:41], v[40:41], v[40:41] op_sel:[0,1] op_sel_hi:[1,0]
	v_cndmask_b32_e64 v39, 1.0, v48, s[42:43]
	v_mov_b32_e32 v61, v40
	v_mul_f32_e32 v45, v39, v40
	v_pk_mul_f32 v[40:41], v[58:59], v[60:61]
	v_cndmask_b32_e64 v37, 1.0, v57, s[42:43]
	v_pk_mul_f32 v[42:43], v[42:43], v[40:41]
	v_mul_f32_e32 v48, v37, v41
	v_mov_b32_e32 v39, v42
	v_mov_b32_e32 v40, v42
	s_nop 1
	v_permlane32_swap_b32_e32 v39, v40
	v_xor_b32_e32 v39, v39, v40
	v_xor_b32_e32 v39, v39, v42
	v_cndmask_b32_e64 v37, 1.0, v39, s[42:43]
	v_mul_f32_e32 v64, v37, v43
	v_mul_f32_e32 v37, v42, v39
	v_xor_b32_e32 v35, v35, v51
	v_mul_f32_e32 v37, v37, v43
	v_mul_f32_e32 v53, v46, v47
	v_pk_mul_f32 v[40:41], v[52:53], v[36:37]
	v_pk_mul_f32 v[42:43], v[50:51], v[34:35]
	v_cndmask_b32_e64 v39, 1.0, v47, s[42:43]
	v_pk_mul_f32 v[42:43], v[42:43], v[40:41]
	v_mul_f32_e32 v57, v39, v37
	v_cndmask_b32_e64 v39, 1.0, v35, s[42:43]
	v_mov_b32_e32 v35, v42
	v_mov_b32_e32 v37, v42
	s_nop 1
	v_permlane32_swap_b32_e32 v35, v37
	v_xor_b32_e32 v35, v35, v37
	v_xor_b32_e32 v35, v35, v42
	v_mul_f32_e32 v39, v39, v41
	v_cndmask_b32_e64 v37, 1.0, v35, s[42:43]
	v_mul_f32_e32 v37, v37, v43
	v_mul_f32_e32 v35, v42, v35
	v_mul_f32_e32 v50, v121, v39
	v_mul_f32_e32 v39, v120, v39
	v_mul_f32_e32 v91, v35, v43
	v_mul_f32_e32 v35, v36, v37
	v_mul_f32_e32 v51, v117, v39
	v_mul_f32_e32 v39, v116, v39
	v_mul_f32_e32 v42, v105, v35
	v_mul_f32_e32 v35, v52, v35
	v_mul_f32_e32 v52, v113, v39
	v_mul_f32_e32 v39, v55, v39
	v_mul_f32_e32 v43, v122, v45
	v_mul_f32_e32 v55, v54, v39
	v_mul_f32_e32 v39, v123, v45
	v_mul_f32_e32 v45, v118, v43
	v_mul_f32_e32 v41, v119, v43
	v_mul_f32_e32 v43, v115, v45
	v_mul_f32_e32 v45, v114, v45
	v_mul_f32_e32 v46, v112, v45
	v_mul_f32_e32 v45, v133, v57
	v_mul_f32_e32 v54, v134, v57
	v_mul_f32_e32 v57, v130, v45
	v_mul_f32_e32 v45, v129, v45
	v_mul_f32_e32 v59, v127, v45
	v_mul_f32_e32 v45, v126, v45
	v_mul_f32_e32 v34, v34, v35
	v_mul_f32_e32 v36, v110, v48
	v_mul_f32_e32 v61, v124, v45
	v_mul_f32_e32 v45, v136, v49
	v_mul_f32_e32 v49, v135, v49
	v_add_u32_e32 v90, s13, v87
	v_mul_f32_e32 v40, v109, v37
	v_mul_f32_e32 v44, v102, v35
	v_mul_f32_e32 v47, v98, v34
	v_mul_f32_e32 v34, v111, v48
	v_mul_f32_e32 v35, v108, v36
	v_mul_f32_e32 v53, v131, v49
	ds_read_b64_tr_b16 v[108:109], v90 offset:8192
	ds_read_b64_tr_b16 v[110:111], v90 offset:8704
	ds_read_b64_tr_b16 v[112:113], v90 offset:12288
	ds_read_b64_tr_b16 v[114:115], v90 offset:12800
	v_mul_f32_e32 v48, v132, v49
	v_mul_f32_e32 v49, v128, v53
	v_mul_f32_e32 v38, v38, v53
	v_mul_f32_e32 v53, v60, v64
	v_mul_f32_e32 v37, v107, v36
	v_mul_f32_e32 v63, v63, v53
	v_mul_f32_e32 v53, v58, v53
	v_mul_f32_e32 v36, v104, v37
	v_mul_f32_e32 v37, v103, v37
	v_mul_f32_e32 v62, v62, v64
	v_mul_f32_e32 v64, v139, v53
	v_mul_f32_e32 v53, v56, v53
	v_mul_f32_e32 v37, v100, v37
	v_mul_f32_e32 v65, v137, v53
	v_mul_f32_e32 v53, v145, v101
	v_mul_f32_e32 v58, v144, v101
	v_cvt_pk_bf16_f32 v100, v47, v44
	v_cvt_pk_bf16_f32 v101, v42, v40
	v_cvt_pk_bf16_f32 v102, v55, v52
	v_cvt_pk_bf16_f32 v103, v51, v50
	v_mul_f32_e32 v38, v125, v38
	v_mul_f32_e32 v60, v142, v58
	s_waitcnt lgkmcnt(2)
	v_mfma_f32_32x32x16_bf16 v[18:33], v[108:111], v[100:103], v[18:33]
	v_mul_f32_e32 v56, v143, v58
	v_mul_f32_e32 v58, v141, v60
	v_mul_f32_e32 v60, v140, v60
	v_mul_f32_e32 v60, v138, v60
	v_cmp_gt_f32_e32 vcc, s8, v91
	s_cmp_eq_u64 vcc, exec
	s_cselect_b64 s[8:9], -1, 0
	s_waitcnt lgkmcnt(0)
	v_mfma_f32_32x32x16_bf16 v[2:17], v[112:115], v[100:103], v[2:17]
	v_cvt_pk_bf16_f32 v102, v65, v64
	v_cvt_pk_bf16_f32 v103, v63, v62
	ds_read_b64_tr_b16 v[62:63], v90 offset:9216
	ds_read_b64_tr_b16 v[64:65], v90 offset:9728
	ds_read_b64_tr_b16 v[108:109], v90 offset:13312
	ds_read_b64_tr_b16 v[110:111], v90 offset:13824
	v_cvt_pk_bf16_f32 v100, v61, v59
	v_cvt_pk_bf16_f32 v101, v57, v54
	s_add_i32 s24, s24, -1
	s_cmp_le_i32 s10, s23
	s_waitcnt lgkmcnt(2)
	v_mfma_f32_32x32x16_bf16 v[18:33], v[62:65], v[100:103], v[18:33]
	v_cvt_pk_bf16_f32 v62, v37, v36
	v_cvt_pk_bf16_f32 v63, v35, v34
	v_cvt_pk_bf16_f32 v64, v46, v43
	v_cvt_pk_bf16_f32 v65, v41, v39
	ds_read_b64_tr_b16 v[34:35], v90 offset:10240
	ds_read_b64_tr_b16 v[36:37], v90 offset:10752
	ds_read_b64_tr_b16 v[40:41], v90 offset:14336
	ds_read_b64_tr_b16 v[42:43], v90 offset:14848
	s_cselect_b64 s[10:11], -1, 0
	s_or_b64 s[10:11], s[8:9], s[10:11]
	s_waitcnt lgkmcnt(4)
	v_mfma_f32_32x32x16_bf16 v[2:17], v[108:111], v[100:103], v[2:17]
	s_sub_i32 s12, s12, 64
	v_add_u32_e32 v87, 0x4000, v87
	s_andn2_b64 vcc, exec, s[10:11]
	s_waitcnt lgkmcnt(2)
	v_mfma_f32_32x32x16_bf16 v[18:33], v[34:37], v[62:65], v[18:33]
	v_cvt_pk_bf16_f32 v34, v38, v49
	v_cvt_pk_bf16_f32 v35, v48, v45
	v_cvt_pk_bf16_f32 v36, v60, v58
	v_cvt_pk_bf16_f32 v37, v56, v53
	s_waitcnt lgkmcnt(0)
	v_mfma_f32_32x32x16_bf16 v[2:17], v[40:43], v[62:65], v[2:17]
	ds_read_b64_tr_b16 v[38:39], v90 offset:11264
	ds_read_b64_tr_b16 v[40:41], v90 offset:11776
	ds_read_b64_tr_b16 v[42:43], v90 offset:15360
	ds_read_b64_tr_b16 v[44:45], v90 offset:15872
	s_waitcnt lgkmcnt(2)
	v_mfma_f32_32x32x16_bf16 v[18:33], v[38:41], v[34:37], v[18:33]
	s_waitcnt lgkmcnt(0)
	v_mfma_f32_32x32x16_bf16 v[2:17], v[42:45], v[34:37], v[2:17]
	s_cbranch_vccnz .LBB0_355

; DI float fast_exp2(float x) { return __builtin_amdgcn_exp2f(x); }
; DI float xhalf_max(float m) { auto rr = __builtin_amdgcn_permlane32_swap(__float_as_uint(m), __float_as_uint(m), false, false); return fmaxf(__uint_as_float(rr[0]), __uint_as_float(rr[1])); }
; DI void moba_softpv(f32x16& c0, f32x16& c1, f32x16& n0, f32x16& n1, bool has_next, bool first, int qpos, int kv0, float& m, float& l, f32x16& o0, f32x16& o1,
;                     float bfar, LAS const float* tab, LAS const unsigned char* Vt, int lane) {
;     ...
;     float tmax = NEG_INF;
; #pragma unroll
;     for (int i = 0; i < 16; ++i) tmax = fmaxf(tmax, fmaxf(c0[i], c1[i]));
;     tmax = xhalf_max(tmax);
;     const bool out_of_band = first ? (fabsf(tmax) > 16.f && tmax > -1e30f) : (tmax > 16.f);
;     if (__ballot(out_of_band) != 0ull) {
;         const float dl = out_of_band ? tmax : 0.f, alpha = first ? 1.0f : fast_exp2(-dl);
;         m += dl; l *= alpha;
; #pragma unroll
;         for (int i = 0; i < 16; ++i) { c0[i] -= dl; c1[i] -= dl; o0[i] *= alpha; o1[i] *= alpha; }
;         if (has_next) {
; #pragma unroll
;             for (int i = 0; i < 16; ++i) { n0[i] -= dl; n1[i] -= dl; }
;         }
;     }
.LBB0_497:
	v_max3_f32 v0, v102, s35, v36
	v_max3_f32 v0, v0, v103, v37
	v_max3_f32 v0, v0, v104, v38
	v_max3_f32 v0, v0, v105, v39
	v_max3_f32 v0, v0, v106, v40
	v_max3_f32 v0, v0, v107, v41
	v_max3_f32 v0, v0, v108, v42
	v_max3_f32 v0, v0, v109, v43
	v_max3_f32 v0, v0, v110, v44
	v_max3_f32 v0, v0, v111, v45
	v_max3_f32 v0, v0, v112, v46
	v_max3_f32 v0, v0, v113, v47
	v_max3_f32 v0, v0, v114, v48
	v_max3_f32 v0, v0, v115, v49
	v_max3_f32 v0, v0, v116, v50
	v_max3_f32 v0, v0, v117, v51
	v_mov_b32_e32 v2, v0
	s_nop 1
	v_permlane32_swap_b32_e32 v0, v2
	v_max_f32_e32 v0, v0, v2
	s_mov_b32 s26, 0xf149f2ca
	v_cmp_gt_f32_e64 s[24:25], |v0|, s90
	v_cmp_lt_f32_e32 vcc, s26, v0
	s_and_b64 s[48:49], vcc, s[24:25]
	v_cndmask_b32_e64 v2, 0, 1, s[46:47]
	v_cmp_ne_u32_e64 s[46:47], 1, v2
	s_mov_b64 vcc, s[48:49]
	s_cbranch_vccz .LBB0_501
	s_and_b64 vcc, exec, s[46:47]
	v_cndmask_b32_e64 v0, 0, v0, s[48:49]
	s_cbranch_vccnz .LBB0_500
	v_sub_f32_e32 v83, v83, v0
	v_sub_f32_e32 v82, v82, v0
	v_sub_f32_e32 v81, v81, v0
	v_sub_f32_e32 v80, v80, v0
	v_sub_f32_e32 v79, v79, v0
	v_sub_f32_e32 v78, v78, v0
	v_sub_f32_e32 v77, v77, v0
	v_sub_f32_e32 v76, v76, v0
	v_sub_f32_e32 v75, v75, v0
	v_sub_f32_e32 v74, v74, v0
	v_sub_f32_e32 v73, v73, v0
	v_sub_f32_e32 v72, v72, v0
	v_sub_f32_e32 v71, v71, v0
	v_sub_f32_e32 v70, v70, v0
	v_sub_f32_e32 v69, v69, v0
	v_sub_f32_e32 v68, v68, v0
	v_sub_f32_e32 v101, v101, v0
	v_sub_f32_e32 v100, v100, v0
	v_sub_f32_e32 v99, v99, v0
	v_sub_f32_e32 v98, v98, v0
	v_sub_f32_e32 v97, v97, v0
	v_sub_f32_e32 v96, v96, v0
	v_sub_f32_e32 v95, v95, v0
	v_sub_f32_e32 v94, v94, v0
	v_sub_f32_e32 v93, v93, v0
	v_sub_f32_e32 v92, v92, v0
	v_sub_f32_e32 v91, v91, v0
	v_sub_f32_e32 v90, v90, v0
	v_sub_f32_e32 v89, v89, v0
	v_sub_f32_e32 v88, v88, v0
	v_sub_f32_e32 v87, v87, v0
	v_sub_f32_e32 v86, v86, v0

; DI float fast_exp2(float x) { return __builtin_amdgcn_exp2f(x); }
; DI float xhalf_max(float m) { auto rr = __builtin_amdgcn_permlane32_swap(__float_as_uint(m), __float_as_uint(m), false, false); return fmaxf(__uint_as_float(rr[0]), __uint_as_float(rr[1])); }
; DI void moba_softpv(f32x16& c0, f32x16& c1, f32x16& n0, f32x16& n1, bool has_next, bool first, int qpos, int kv0, float& m, float& l, f32x16& o0, f32x16& o1,
;                     float bfar, LAS const float* tab, LAS const unsigned char* Vt, int lane) {
;     ...
;     float tmax = NEG_INF;
; #pragma unroll
;     for (int i = 0; i < 16; ++i) tmax = fmaxf(tmax, fmaxf(c0[i], c1[i]));
;     tmax = xhalf_max(tmax);
;     const bool out_of_band = first ? (fabsf(tmax) > 16.f && tmax > -1e30f) : (tmax > 16.f);
;     if (__ballot(out_of_band) != 0ull) {
;         const float dl = out_of_band ? tmax : 0.f, alpha = first ? 1.0f : fast_exp2(-dl);
;         m += dl; l *= alpha;
; #pragma unroll
;         for (int i = 0; i < 16; ++i) { c0[i] -= dl; c1[i] -= dl; o0[i] *= alpha; o1[i] *= alpha; }
;         if (has_next) {
; #pragma unroll
;             for (int i = 0; i < 16; ++i) { n0[i] -= dl; n1[i] -= dl; }
;         }
;     }
.LBB0_507:
	v_max3_f32 v0, v86, s35, v68
	v_max3_f32 v0, v0, v87, v69
	v_max3_f32 v0, v0, v88, v70
	v_max3_f32 v0, v0, v89, v71
	v_max3_f32 v0, v0, v90, v72
	v_max3_f32 v0, v0, v91, v73
	v_max3_f32 v0, v0, v92, v74
	v_max3_f32 v0, v0, v93, v75
	v_max3_f32 v0, v0, v94, v76
	v_max3_f32 v0, v0, v95, v77
	v_max3_f32 v0, v0, v96, v78
	v_max3_f32 v0, v0, v97, v79
	v_max3_f32 v0, v0, v98, v80
	v_max3_f32 v0, v0, v99, v81
	v_max3_f32 v0, v0, v100, v82
	v_max3_f32 v0, v0, v101, v83
	v_mov_b32_e32 v84, v0
	s_nop 1
	v_permlane32_swap_b32_e32 v0, v84
	v_max_f32_e32 v0, v0, v84
	v_cmp_lt_f32_e64 s[48:49], s90, v0
	v_cndmask_b32_e64 v84, 0, 1, s[46:47]
	v_cmp_ne_u32_e64 s[46:47], 1, v84
	s_mov_b64 vcc, s[48:49]
	s_cbranch_vccz .LBB0_511
	s_and_b64 vcc, exec, s[46:47]
	v_cndmask_b32_e64 v0, 0, v0, s[48:49]
	s_cbranch_vccnz .LBB0_510
	v_sub_f32_e32 v67, v67, v0
	v_sub_f32_e32 v66, v66, v0
	v_sub_f32_e32 v65, v65, v0
	v_sub_f32_e32 v64, v64, v0
	v_sub_f32_e32 v63, v63, v0
	v_sub_f32_e32 v62, v62, v0
	v_sub_f32_e32 v61, v61, v0
	v_sub_f32_e32 v60, v60, v0
	v_sub_f32_e32 v59, v59, v0
	v_sub_f32_e32 v58, v58, v0
	v_sub_f32_e32 v57, v57, v0
	v_sub_f32_e32 v56, v56, v0
	v_sub_f32_e32 v55, v55, v0
	v_sub_f32_e32 v54, v54, v0
	v_sub_f32_e32 v53, v53, v0
	v_sub_f32_e32 v52, v52, v0
	v_sub_f32_e32 v51, v51, v0
	v_sub_f32_e32 v50, v50, v0
	v_sub_f32_e32 v49, v49, v0
	v_sub_f32_e32 v48, v48, v0
	v_sub_f32_e32 v47, v47, v0
	v_sub_f32_e32 v46, v46, v0
	v_sub_f32_e32 v45, v45, v0
	v_sub_f32_e32 v44, v44, v0
	v_sub_f32_e32 v43, v43, v0
	v_sub_f32_e32 v42, v42, v0
	v_sub_f32_e32 v41, v41, v0
	v_sub_f32_e32 v40, v40, v0
	v_sub_f32_e32 v39, v39, v0
	v_sub_f32_e32 v38, v38, v0
	v_sub_f32_e32 v37, v37, v0
	v_sub_f32_e32 v36, v36, v0

; DI float fast_exp2(float x) { return __builtin_amdgcn_exp2f(x); }
; DI float xhalf_max(float m) { auto rr = __builtin_amdgcn_permlane32_swap(__float_as_uint(m), __float_as_uint(m), false, false); return fmaxf(__uint_as_float(rr[0]), __uint_as_float(rr[1])); }
; DI void moba_softpv(f32x16& c0, f32x16& c1, f32x16& n0, f32x16& n1, bool has_next, bool first, int qpos, int kv0, float& m, float& l, f32x16& o0, f32x16& o1,
;                     float bfar, LAS const float* tab, LAS const unsigned char* Vt, int lane) {
;     ...
;     float tmax = NEG_INF;
; #pragma unroll
;     for (int i = 0; i < 16; ++i) tmax = fmaxf(tmax, fmaxf(c0[i], c1[i]));
;     tmax = xhalf_max(tmax);
;     const bool out_of_band = first ? (fabsf(tmax) > 16.f && tmax > -1e30f) : (tmax > 16.f);
;     if (__ballot(out_of_band) != 0ull) {
;         const float dl = out_of_band ? tmax : 0.f, alpha = first ? 1.0f : fast_exp2(-dl);
;         m += dl; l *= alpha;
; #pragma unroll
;         for (int i = 0; i < 16; ++i) { c0[i] -= dl; c1[i] -= dl; o0[i] *= alpha; o1[i] *= alpha; }
;         if (has_next) {
; #pragma unroll
;             for (int i = 0; i < 16; ++i) { n0[i] -= dl; n1[i] -= dl; }
;         }
;     }
.LBB0_516:
	v_max3_f32 v0, v36, s35, v52
	v_max3_f32 v0, v0, v37, v53
	v_max3_f32 v0, v0, v38, v54
	v_max3_f32 v0, v0, v39, v55
	v_max3_f32 v0, v0, v40, v56
	v_max3_f32 v0, v0, v41, v57
	v_max3_f32 v0, v0, v42, v58
	v_max3_f32 v0, v0, v43, v59
	v_max3_f32 v0, v0, v44, v60
	v_max3_f32 v0, v0, v45, v61
	v_max3_f32 v0, v0, v46, v62
	v_max3_f32 v0, v0, v47, v63
	v_max3_f32 v0, v0, v48, v64
	v_max3_f32 v0, v0, v49, v65
	v_max3_f32 v0, v0, v50, v66
	v_max3_f32 v0, v0, v51, v67
	v_mov_b32_e32 v100, v0
	s_nop 1
	v_permlane32_swap_b32_e32 v0, v100
	v_max_f32_e32 v0, v0, v100
	v_cmp_lt_f32_e64 s[48:49], s90, v0
	v_cndmask_b32_e64 v100, 0, 1, s[46:47]
	v_cmp_ne_u32_e64 s[46:47], 1, v100
	s_mov_b64 vcc, s[48:49]
	s_cbranch_vccz .LBB0_520
	s_and_b64 vcc, exec, s[46:47]
	v_cndmask_b32_e64 v0, 0, v0, s[48:49]
	s_cbranch_vccnz .LBB0_519
	v_sub_f32_e32 v99, v99, v0
	v_sub_f32_e32 v98, v98, v0
	v_sub_f32_e32 v97, v97, v0
	v_sub_f32_e32 v96, v96, v0
	v_sub_f32_e32 v95, v95, v0
	v_sub_f32_e32 v94, v94, v0
	v_sub_f32_e32 v93, v93, v0
	v_sub_f32_e32 v92, v92, v0
	v_sub_f32_e32 v91, v91, v0
	v_sub_f32_e32 v90, v90, v0
	v_sub_f32_e32 v89, v89, v0
	v_sub_f32_e32 v88, v88, v0
	v_sub_f32_e32 v87, v87, v0
	v_sub_f32_e32 v86, v86, v0
	v_sub_f32_e32 v85, v85, v0
	v_sub_f32_e32 v84, v84, v0
	v_sub_f32_e32 v83, v83, v0
	v_sub_f32_e32 v82, v82, v0
	v_sub_f32_e32 v81, v81, v0
	v_sub_f32_e32 v80, v80, v0
	v_sub_f32_e32 v79, v79, v0
	v_sub_f32_e32 v78, v78, v0
	v_sub_f32_e32 v77, v77, v0
	v_sub_f32_e32 v76, v76, v0
	v_sub_f32_e32 v75, v75, v0
	v_sub_f32_e32 v74, v74, v0
	v_sub_f32_e32 v73, v73, v0
	v_sub_f32_e32 v72, v72, v0
	v_sub_f32_e32 v71, v71, v0
	v_sub_f32_e32 v70, v70, v0
	v_sub_f32_e32 v69, v69, v0
	v_sub_f32_e32 v68, v68, v0

; DI float fast_exp2(float x) { return __builtin_amdgcn_exp2f(x); }
; DI float xhalf_max(float m) { auto rr = __builtin_amdgcn_permlane32_swap(__float_as_uint(m), __float_as_uint(m), false, false); return fmaxf(__uint_as_float(rr[0]), __uint_as_float(rr[1])); }
; DI void moba_softpv(f32x16& c0, f32x16& c1, f32x16& n0, f32x16& n1, bool has_next, bool first, int qpos, int kv0, float& m, float& l, f32x16& o0, f32x16& o1,
;                     float bfar, LAS const float* tab, LAS const unsigned char* Vt, int lane) {
;     ...
;     float tmax = NEG_INF;
; #pragma unroll
;     for (int i = 0; i < 16; ++i) tmax = fmaxf(tmax, fmaxf(c0[i], c1[i]));
;     tmax = xhalf_max(tmax);
;     const bool out_of_band = first ? (fabsf(tmax) > 16.f && tmax > -1e30f) : (tmax > 16.f);
;     if (__ballot(out_of_band) != 0ull) {
;         const float dl = out_of_band ? tmax : 0.f, alpha = first ? 1.0f : fast_exp2(-dl);
;         m += dl; l *= alpha;
; #pragma unroll
;         for (int i = 0; i < 16; ++i) { c0[i] -= dl; c1[i] -= dl; o0[i] *= alpha; o1[i] *= alpha; }
;         if (has_next) {
; #pragma unroll
;             for (int i = 0; i < 16; ++i) { n0[i] -= dl; n1[i] -= dl; }
;         }
;     }
;     float ls = 0.f;
; #pragma unroll
;     for (int i = 0; i < 16; ++i) { c0[i] = fast_exp2(c0[i]); c1[i] = fast_exp2(c1[i]); ls += c0[i] + c1[i]; }
;     l += ls;
;     pv_tile(o0, o1, Vt, c0, c1, lane);
.LBB0_523:
	v_max3_f32 v0, v68, s35, v84
	v_max3_f32 v0, v0, v69, v85
	v_max3_f32 v0, v0, v70, v86
	v_max3_f32 v0, v0, v71, v87
	v_max3_f32 v0, v0, v72, v88
	v_max3_f32 v0, v0, v73, v89
	v_max3_f32 v0, v0, v74, v90
	v_max3_f32 v0, v0, v75, v91
	v_max3_f32 v0, v0, v76, v92
	v_max3_f32 v0, v0, v77, v93
	v_max3_f32 v0, v0, v78, v94
	v_max3_f32 v0, v0, v79, v95
	v_max3_f32 v0, v0, v80, v96
	v_max3_f32 v0, v0, v81, v97
	v_max3_f32 v0, v0, v82, v98
	v_max3_f32 v0, v0, v83, v99
	v_mov_b32_e32 v18, v0
	s_nop 1
	v_permlane32_swap_b32_e32 v0, v18
	v_max_f32_e32 v0, v0, v18
	v_cmp_lt_f32_e32 vcc, s90, v0
	s_cbranch_vccz .LBB0_525
	s_nop 0
	v_cndmask_b32_e32 v0, 0, v0, vcc
	v_exp_f32_e64 v18, -v0
	v_add_f32_e32 v150, v150, v0
	v_pk_add_f32 v[84:85], v[84:85], v[0:1] op_sel_hi:[1,0] neg_lo:[0,1] neg_hi:[0,1]
	v_pk_add_f32 v[68:69], v[68:69], v[0:1] op_sel_hi:[1,0] neg_lo:[0,1] neg_hi:[0,1]
	v_mul_f32_e32 v137, v137, v18
	v_pk_add_f32 v[86:87], v[86:87], v[0:1] op_sel_hi:[1,0] neg_lo:[0,1] neg_hi:[0,1]
	v_pk_add_f32 v[70:71], v[70:71], v[0:1] op_sel_hi:[1,0] neg_lo:[0,1] neg_hi:[0,1]
	v_pk_add_f32 v[88:89], v[88:89], v[0:1] op_sel_hi:[1,0] neg_lo:[0,1] neg_hi:[0,1]
	v_pk_add_f32 v[72:73], v[72:73], v[0:1] op_sel_hi:[1,0] neg_lo:[0,1] neg_hi:[0,1]
	v_pk_add_f32 v[90:91], v[90:91], v[0:1] op_sel_hi:[1,0] neg_lo:[0,1] neg_hi:[0,1]
	v_pk_add_f32 v[74:75], v[74:75], v[0:1] op_sel_hi:[1,0] neg_lo:[0,1] neg_hi:[0,1]
	v_pk_add_f32 v[92:93], v[92:93], v[0:1] op_sel_hi:[1,0] neg_lo:[0,1] neg_hi:[0,1]
	v_pk_add_f32 v[76:77], v[76:77], v[0:1] op_sel_hi:[1,0] neg_lo:[0,1] neg_hi:[0,1]
	v_pk_add_f32 v[94:95], v[94:95], v[0:1] op_sel_hi:[1,0] neg_lo:[0,1] neg_hi:[0,1]
	v_pk_add_f32 v[78:79], v[78:79], v[0:1] op_sel_hi:[1,0] neg_lo:[0,1] neg_hi:[0,1]
	v_pk_add_f32 v[96:97], v[96:97], v[0:1] op_sel_hi:[1,0] neg_lo:[0,1] neg_hi:[0,1]
	v_pk_add_f32 v[80:81], v[80:81], v[0:1] op_sel_hi:[1,0] neg_lo:[0,1] neg_hi:[0,1]
	v_pk_add_f32 v[98:99], v[98:99], v[0:1] op_sel_hi:[1,0] neg_lo:[0,1] neg_hi:[0,1]
	v_pk_add_f32 v[82:83], v[82:83], v[0:1] op_sel_hi:[1,0] neg_lo:[0,1] neg_hi:[0,1]
	v_pk_mul_f32 v[34:35], v[34:35], v[18:19] op_sel_hi:[1,0]
	v_pk_mul_f32 v[32:33], v[32:33], v[18:19] op_sel_hi:[1,0]
	v_pk_mul_f32 v[30:31], v[30:31], v[18:19] op_sel_hi:[1,0]
	v_pk_mul_f32 v[28:29], v[28:29], v[18:19] op_sel_hi:[1,0]
	v_pk_mul_f32 v[26:27], v[26:27], v[18:19] op_sel_hi:[1,0]
	v_pk_mul_f32 v[24:25], v[24:25], v[18:19] op_sel_hi:[1,0]
	v_pk_mul_f32 v[22:23], v[22:23], v[18:19] op_sel_hi:[1,0]
	v_pk_mul_f32 v[20:21], v[20:21], v[18:19] op_sel_hi:[1,0]
	v_pk_mul_f32 v[16:17], v[16:17], v[18:19] op_sel_hi:[1,0]
	v_pk_mul_f32 v[14:15], v[14:15], v[18:19] op_sel_hi:[1,0]
	v_pk_mul_f32 v[12:13], v[12:13], v[18:19] op_sel_hi:[1,0]
	v_pk_mul_f32 v[10:11], v[10:11], v[18:19] op_sel_hi:[1,0]
	v_pk_mul_f32 v[8:9], v[8:9], v[18:19] op_sel_hi:[1,0]
	v_pk_mul_f32 v[6:7], v[6:7], v[18:19] op_sel_hi:[1,0]
	v_pk_mul_f32 v[4:5], v[4:5], v[18:19] op_sel_hi:[1,0]
	v_pk_mul_f32 v[2:3], v[2:3], v[18:19] op_sel_hi:[1,0]
